# also removed the redundant post-barrier lgkmcnt wait and the no-op mid-segment setprio pair in the three K-loops
# speedup vs baseline: 1.0041x; 1.0041x over previous
.LBB0_256:
	s_add_u32 s22, s2, 0xfff80080
	s_addc_u32 s23, s3, -1
	s_add_i32 s48, 0, 0x10000
	s_cmp_eq_u32 s35, 28
	s_cselect_b32 s27, s8, s23
	s_cselect_b32 s26, s9, s22
	s_cselect_b32 s23, s15, s34
	s_cselect_b32 s22, s17, s33
	s_add_i32 s50, 0, 0x14000
	v_add_u32_e32 v176, s48, v191
	v_add_u32_e32 v188, s50, v191
	ds_read_b128 v[148:151], v176
	ds_read_b128 v[152:155], v176 offset:1024
	ds_read_b128 v[172:175], v176 offset:2048
	ds_read_b128 v[176:179], v176 offset:3072
	ds_read_b128 v[180:183], v188
	ds_read_b128 v[184:187], v188 offset:1024
	ds_read_b128 v[196:199], v188 offset:2048
	ds_read_b128 v[200:203], v188 offset:3072
	v_lshl_add_u64 v[188:189], s[2:3], 0, v[168:169]
	s_add_i32 m0, s39, 0xc000
	ds_read_b128 v[204:207], v194
	ds_read_b128 v[212:215], v194 offset:1024
	ds_read_b128 v[216:219], v194 offset:2048
	ds_read_b128 v[220:223], v194 offset:3072
	ds_read_b128 v[224:227], v194 offset:4096
	ds_read_b128 v[228:231], v194 offset:5120
	ds_read_b128 v[232:235], v194 offset:6144
	ds_read_b128 v[236:239], v194 offset:7168
	global_load_lds_dwordx4 v[188:189], off
	v_lshl_add_u64 v[188:189], s[2:3], 0, v[170:171]
	s_add_i32 m0, s39, 0xe000
	s_nop 0
	global_load_lds_dwordx4 v[188:189], off
	s_waitcnt vmcnt(8)
	s_waitcnt lgkmcnt(0)
	s_barrier
	s_setprio 1
	v_mfma_f32_16x16x32_bf16 v[144:147], v[148:151], v[204:207], v[144:147]
	v_mfma_f32_16x16x32_bf16 v[136:139], v[172:175], v[204:207], v[136:139]
	v_mfma_f32_16x16x32_bf16 v[128:131], v[148:151], v[216:219], v[128:131]
	v_mfma_f32_16x16x32_bf16 v[120:123], v[172:175], v[216:219], v[120:123]
	v_mfma_f32_16x16x32_bf16 v[112:115], v[148:151], v[224:227], v[112:115]
	v_mfma_f32_16x16x32_bf16 v[104:107], v[172:175], v[224:227], v[104:107]
	v_mfma_f32_16x16x32_bf16 v[96:99], v[148:151], v[232:235], v[96:99]
	v_mfma_f32_16x16x32_bf16 v[88:91], v[172:175], v[232:235], v[88:91]
	v_mfma_f32_16x16x32_bf16 v[144:147], v[152:155], v[212:215], v[144:147]
	v_mfma_f32_16x16x32_bf16 v[136:139], v[176:179], v[212:215], v[136:139]
	v_mfma_f32_16x16x32_bf16 v[128:131], v[152:155], v[220:223], v[128:131]
	v_mfma_f32_16x16x32_bf16 v[120:123], v[176:179], v[220:223], v[120:123]
	v_mfma_f32_16x16x32_bf16 v[112:115], v[152:155], v[228:231], v[112:115]
	v_mfma_f32_16x16x32_bf16 v[104:107], v[176:179], v[228:231], v[104:107]
	v_mfma_f32_16x16x32_bf16 v[96:99], v[152:155], v[236:239], v[96:99]
	v_mfma_f32_16x16x32_bf16 v[88:91], v[176:179], v[236:239], v[88:91]
	v_mfma_f32_16x16x32_bf16 v[140:143], v[180:183], v[204:207], v[140:143]
	v_mfma_f32_16x16x32_bf16 v[132:135], v[196:199], v[204:207], v[132:135]
	v_mfma_f32_16x16x32_bf16 v[124:127], v[180:183], v[216:219], v[124:127]
	v_mfma_f32_16x16x32_bf16 v[116:119], v[196:199], v[216:219], v[116:119]
	v_mfma_f32_16x16x32_bf16 v[108:111], v[180:183], v[224:227], v[108:111]
	v_mfma_f32_16x16x32_bf16 v[100:103], v[196:199], v[224:227], v[100:103]
	v_mfma_f32_16x16x32_bf16 v[92:95], v[180:183], v[232:235], v[92:95]
	v_mfma_f32_16x16x32_bf16 v[84:87], v[196:199], v[232:235], v[84:87]
	v_mfma_f32_16x16x32_bf16 v[140:143], v[184:187], v[212:215], v[140:143]
	v_mfma_f32_16x16x32_bf16 v[132:135], v[200:203], v[212:215], v[132:135]
	v_mfma_f32_16x16x32_bf16 v[124:127], v[184:187], v[220:223], v[124:127]
	v_mfma_f32_16x16x32_bf16 v[116:119], v[200:203], v[220:223], v[116:119]
	v_mfma_f32_16x16x32_bf16 v[108:111], v[184:187], v[228:231], v[108:111]
	v_mfma_f32_16x16x32_bf16 v[100:103], v[200:203], v[228:231], v[100:103]
	v_mfma_f32_16x16x32_bf16 v[92:95], v[184:187], v[236:239], v[92:95]
	v_mfma_f32_16x16x32_bf16 v[84:87], v[200:203], v[236:239], v[84:87]
	s_setprio 0
	s_barrier
	s_add_i32 s48, s48, s28
	v_lshl_add_u64 v[188:189], s[22:23], 0, v[2:3]
	s_mov_b32 m0, s48
	ds_read_b128 v[204:207], v194 offset:16384
	ds_read_b128 v[212:215], v194 offset:17408
	ds_read_b128 v[216:219], v194 offset:18432
	ds_read_b128 v[220:223], v194 offset:19456
	ds_read_b128 v[224:227], v194 offset:20480
	ds_read_b128 v[228:231], v194 offset:21504
	ds_read_b128 v[232:235], v194 offset:22528
	ds_read_b128 v[236:239], v194 offset:23552
	global_load_lds_dwordx4 v[188:189], off
	s_add_i32 m0, s48, 0x2000
	s_add_u32 s48, s22, 0x80000
	v_lshl_add_u64 v[240:241], s[22:23], 0, v[156:157]
	s_addc_u32 s49, s23, 0
	s_add_i32 s50, s50, s28
	global_load_lds_dwordx4 v[240:241], off
	v_lshl_add_u64 v[242:243], s[48:49], 0, v[2:3]
	s_mov_b32 m0, s50
	v_lshl_add_u64 v[244:245], s[26:27], 0, v[158:159]
	global_load_lds_dwordx4 v[242:243], off
	v_lshl_add_u64 v[242:243], s[48:49], 0, v[156:157]
	s_add_i32 m0, s50, 0x2000
	s_nop 0
	global_load_lds_dwordx4 v[242:243], off
	v_lshl_add_u64 v[242:243], s[26:27], 0, v[160:161]
	s_mov_b32 m0, s39
	s_nop 0
	global_load_lds_dwordx4 v[242:243], off
	s_mov_b32 m0, s41
	s_nop 0
	global_load_lds_dwordx4 v[244:245], off
	s_waitcnt vmcnt(8)
	s_waitcnt lgkmcnt(0)
	s_barrier
	s_setprio 1
	v_mfma_f32_16x16x32_bf16 v[80:83], v[148:151], v[204:207], v[80:83]
	v_mfma_f32_16x16x32_bf16 v[72:75], v[172:175], v[204:207], v[72:75]
	v_mfma_f32_16x16x32_bf16 v[64:67], v[148:151], v[216:219], v[64:67]
	v_mfma_f32_16x16x32_bf16 v[56:59], v[172:175], v[216:219], v[56:59]
	v_mfma_f32_16x16x32_bf16 v[48:51], v[148:151], v[224:227], v[48:51]
	v_mfma_f32_16x16x32_bf16 v[40:43], v[172:175], v[224:227], v[40:43]
	v_mfma_f32_16x16x32_bf16 v[32:35], v[148:151], v[232:235], v[32:35]
	v_mfma_f32_16x16x32_bf16 v[24:27], v[172:175], v[232:235], v[24:27]
	v_mfma_f32_16x16x32_bf16 v[80:83], v[152:155], v[212:215], v[80:83]
	v_mfma_f32_16x16x32_bf16 v[72:75], v[176:179], v[212:215], v[72:75]
	v_mfma_f32_16x16x32_bf16 v[64:67], v[152:155], v[220:223], v[64:67]
	v_mfma_f32_16x16x32_bf16 v[56:59], v[176:179], v[220:223], v[56:59]
	v_mfma_f32_16x16x32_bf16 v[48:51], v[152:155], v[228:231], v[48:51]
	v_mfma_f32_16x16x32_bf16 v[40:43], v[176:179], v[228:231], v[40:43]
	v_mfma_f32_16x16x32_bf16 v[32:35], v[152:155], v[236:239], v[32:35]
	v_mfma_f32_16x16x32_bf16 v[24:27], v[176:179], v[236:239], v[24:27]
	v_mfma_f32_16x16x32_bf16 v[76:79], v[180:183], v[204:207], v[76:79]
	v_mfma_f32_16x16x32_bf16 v[68:71], v[196:199], v[204:207], v[68:71]
	v_mfma_f32_16x16x32_bf16 v[60:63], v[180:183], v[216:219], v[60:63]
	v_mfma_f32_16x16x32_bf16 v[52:55], v[196:199], v[216:219], v[52:55]
	v_mfma_f32_16x16x32_bf16 v[44:47], v[180:183], v[224:227], v[44:47]
	v_mfma_f32_16x16x32_bf16 v[36:39], v[196:199], v[224:227], v[36:39]
	v_mfma_f32_16x16x32_bf16 v[28:31], v[180:183], v[232:235], v[28:31]
	v_mfma_f32_16x16x32_bf16 v[20:23], v[196:199], v[232:235], v[20:23]
	v_mfma_f32_16x16x32_bf16 v[76:79], v[184:187], v[212:215], v[76:79]
	v_mfma_f32_16x16x32_bf16 v[68:71], v[200:203], v[212:215], v[68:71]
	v_mfma_f32_16x16x32_bf16 v[60:63], v[184:187], v[220:223], v[60:63]
	v_mfma_f32_16x16x32_bf16 v[52:55], v[200:203], v[220:223], v[52:55]
	v_mfma_f32_16x16x32_bf16 v[44:47], v[184:187], v[228:231], v[44:47]
	v_mfma_f32_16x16x32_bf16 v[36:39], v[200:203], v[228:231], v[36:39]
	v_mfma_f32_16x16x32_bf16 v[28:31], v[184:187], v[236:239], v[28:31]
	v_mfma_f32_16x16x32_bf16 v[20:23], v[200:203], v[236:239], v[20:23]
	s_setprio 0
	s_barrier
	s_add_i32 s48, 0, 0x18000
	s_add_i32 s49, 0, 0x1c000
	v_add_u32_e32 v176, s48, v191
	v_add_u32_e32 v195, s49, v191
	ds_read_b128 v[148:151], v176
	ds_read_b128 v[152:155], v176 offset:1024
	ds_read_b128 v[172:175], v176 offset:2048
	ds_read_b128 v[176:179], v176 offset:3072
	ds_read_b128 v[180:183], v195
	ds_read_b128 v[184:187], v195 offset:1024
	ds_read_b128 v[196:199], v195 offset:2048
	ds_read_b128 v[200:203], v195 offset:3072
	s_add_u32 s26, s26, 0x80000
	s_addc_u32 s27, s27, 0
	s_mov_b32 m0, s42
	v_lshl_add_u64 v[246:247], s[26:27], 0, v[160:161]
	ds_read_b128 v[204:207], v194 offset:32768
	ds_read_b128 v[212:215], v194 offset:33792
	ds_read_b128 v[216:219], v194 offset:34816
	ds_read_b128 v[220:223], v194 offset:35840
	ds_read_b128 v[224:227], v194 offset:36864
	ds_read_b128 v[228:231], v194 offset:37888
	ds_read_b128 v[232:235], v194 offset:38912
	ds_read_b128 v[236:239], v194 offset:39936
	global_load_lds_dwordx4 v[246:247], off
	v_lshl_add_u64 v[246:247], s[26:27], 0, v[158:159]
	s_mov_b32 m0, s43
	s_nop 0
	global_load_lds_dwordx4 v[246:247], off
	s_waitcnt vmcnt(8)
	s_waitcnt lgkmcnt(0)
	s_barrier
	s_setprio 1
	v_mfma_f32_16x16x32_bf16 v[144:147], v[148:151], v[204:207], v[144:147]
	v_mfma_f32_16x16x32_bf16 v[136:139], v[172:175], v[204:207], v[136:139]
	v_mfma_f32_16x16x32_bf16 v[128:131], v[148:151], v[216:219], v[128:131]
	v_mfma_f32_16x16x32_bf16 v[120:123], v[172:175], v[216:219], v[120:123]
	v_mfma_f32_16x16x32_bf16 v[112:115], v[148:151], v[224:227], v[112:115]
	v_mfma_f32_16x16x32_bf16 v[104:107], v[172:175], v[224:227], v[104:107]
	v_mfma_f32_16x16x32_bf16 v[96:99], v[148:151], v[232:235], v[96:99]
	v_mfma_f32_16x16x32_bf16 v[88:91], v[172:175], v[232:235], v[88:91]
	v_mfma_f32_16x16x32_bf16 v[144:147], v[152:155], v[212:215], v[144:147]
	v_mfma_f32_16x16x32_bf16 v[136:139], v[176:179], v[212:215], v[136:139]
	v_mfma_f32_16x16x32_bf16 v[128:131], v[152:155], v[220:223], v[128:131]
	v_mfma_f32_16x16x32_bf16 v[120:123], v[176:179], v[220:223], v[120:123]
	v_mfma_f32_16x16x32_bf16 v[112:115], v[152:155], v[228:231], v[112:115]
	v_mfma_f32_16x16x32_bf16 v[104:107], v[176:179], v[228:231], v[104:107]
	v_mfma_f32_16x16x32_bf16 v[96:99], v[152:155], v[236:239], v[96:99]
	v_mfma_f32_16x16x32_bf16 v[88:91], v[176:179], v[236:239], v[88:91]
	v_mfma_f32_16x16x32_bf16 v[140:143], v[180:183], v[204:207], v[140:143]
	v_mfma_f32_16x16x32_bf16 v[132:135], v[196:199], v[204:207], v[132:135]
	v_mfma_f32_16x16x32_bf16 v[124:127], v[180:183], v[216:219], v[124:127]
	v_mfma_f32_16x16x32_bf16 v[116:119], v[196:199], v[216:219], v[116:119]
	v_mfma_f32_16x16x32_bf16 v[108:111], v[180:183], v[224:227], v[108:111]
	v_mfma_f32_16x16x32_bf16 v[100:103], v[196:199], v[224:227], v[100:103]
	v_mfma_f32_16x16x32_bf16 v[92:95], v[180:183], v[232:235], v[92:95]
	v_mfma_f32_16x16x32_bf16 v[84:87], v[196:199], v[232:235], v[84:87]
	v_mfma_f32_16x16x32_bf16 v[140:143], v[184:187], v[212:215], v[140:143]
	v_mfma_f32_16x16x32_bf16 v[132:135], v[200:203], v[212:215], v[132:135]
	v_mfma_f32_16x16x32_bf16 v[124:127], v[184:187], v[220:223], v[124:127]
	v_mfma_f32_16x16x32_bf16 v[116:119], v[200:203], v[220:223], v[116:119]
	v_mfma_f32_16x16x32_bf16 v[108:111], v[184:187], v[228:231], v[108:111]
	v_mfma_f32_16x16x32_bf16 v[100:103], v[200:203], v[228:231], v[100:103]
	v_mfma_f32_16x16x32_bf16 v[92:95], v[184:187], v[236:239], v[92:95]
	v_mfma_f32_16x16x32_bf16 v[84:87], v[200:203], v[236:239], v[84:87]
	s_setprio 0
	s_barrier
	s_add_i32 s26, s48, s28
	v_lshl_add_u64 v[188:189], v[188:189], 0, s[30:31]
	s_mov_b32 m0, s26
	ds_read_b128 v[204:207], v194 offset:49152
	ds_read_b128 v[212:215], v194 offset:50176
	ds_read_b128 v[216:219], v194 offset:51200
	ds_read_b128 v[220:223], v194 offset:52224
	ds_read_b128 v[224:227], v194 offset:53248
	ds_read_b128 v[228:231], v194 offset:54272
	ds_read_b128 v[232:235], v194 offset:55296
	ds_read_b128 v[236:239], v194 offset:56320
	global_load_lds_dwordx4 v[188:189], off
	s_add_i32 m0, s26, 0x2000
	s_add_u32 s22, s22, 0x80080
	v_lshl_add_u64 v[188:189], v[240:241], 0, s[30:31]
	s_addc_u32 s23, s23, 0
	s_add_i32 s26, s49, s28
	global_load_lds_dwordx4 v[188:189], off
	v_lshl_add_u64 v[188:189], s[22:23], 0, v[2:3]
	s_mov_b32 m0, s26
	s_nop 0
	global_load_lds_dwordx4 v[188:189], off
	v_lshl_add_u64 v[188:189], s[22:23], 0, v[156:157]
	s_add_i32 m0, s26, 0x2000
	s_nop 0
	global_load_lds_dwordx4 v[188:189], off
	v_lshl_add_u64 v[188:189], v[242:243], 0, s[30:31]
	s_mov_b32 m0, s44
	s_nop 0
	global_load_lds_dwordx4 v[188:189], off
	v_lshl_add_u64 v[188:189], v[244:245], 0, s[30:31]
	s_mov_b32 m0, s45
	s_nop 0
	global_load_lds_dwordx4 v[188:189], off
	s_waitcnt vmcnt(8)
	s_waitcnt lgkmcnt(0)
	s_barrier
	s_setprio 1
	v_mfma_f32_16x16x32_bf16 v[80:83], v[148:151], v[204:207], v[80:83]
	v_mfma_f32_16x16x32_bf16 v[72:75], v[172:175], v[204:207], v[72:75]
	v_mfma_f32_16x16x32_bf16 v[64:67], v[148:151], v[216:219], v[64:67]
	v_mfma_f32_16x16x32_bf16 v[56:59], v[172:175], v[216:219], v[56:59]
	v_mfma_f32_16x16x32_bf16 v[48:51], v[148:151], v[224:227], v[48:51]
	v_mfma_f32_16x16x32_bf16 v[40:43], v[172:175], v[224:227], v[40:43]
	v_mfma_f32_16x16x32_bf16 v[32:35], v[148:151], v[232:235], v[32:35]
	v_mfma_f32_16x16x32_bf16 v[24:27], v[172:175], v[232:235], v[24:27]
	v_mfma_f32_16x16x32_bf16 v[80:83], v[152:155], v[212:215], v[80:83]
	v_mfma_f32_16x16x32_bf16 v[72:75], v[176:179], v[212:215], v[72:75]
	v_mfma_f32_16x16x32_bf16 v[64:67], v[152:155], v[220:223], v[64:67]
	v_mfma_f32_16x16x32_bf16 v[56:59], v[176:179], v[220:223], v[56:59]
	v_mfma_f32_16x16x32_bf16 v[48:51], v[152:155], v[228:231], v[48:51]
	v_mfma_f32_16x16x32_bf16 v[40:43], v[176:179], v[228:231], v[40:43]
	v_mfma_f32_16x16x32_bf16 v[32:35], v[152:155], v[236:239], v[32:35]
	v_mfma_f32_16x16x32_bf16 v[24:27], v[176:179], v[236:239], v[24:27]
	v_mfma_f32_16x16x32_bf16 v[76:79], v[180:183], v[204:207], v[76:79]
	v_mfma_f32_16x16x32_bf16 v[68:71], v[196:199], v[204:207], v[68:71]
	v_mfma_f32_16x16x32_bf16 v[60:63], v[180:183], v[216:219], v[60:63]
	v_mfma_f32_16x16x32_bf16 v[52:55], v[196:199], v[216:219], v[52:55]
	v_mfma_f32_16x16x32_bf16 v[44:47], v[180:183], v[224:227], v[44:47]
	v_mfma_f32_16x16x32_bf16 v[36:39], v[196:199], v[224:227], v[36:39]
	v_mfma_f32_16x16x32_bf16 v[28:31], v[180:183], v[232:235], v[28:31]
	v_mfma_f32_16x16x32_bf16 v[20:23], v[196:199], v[232:235], v[20:23]
	v_mfma_f32_16x16x32_bf16 v[76:79], v[184:187], v[212:215], v[76:79]
	v_mfma_f32_16x16x32_bf16 v[68:71], v[200:203], v[212:215], v[68:71]
	v_mfma_f32_16x16x32_bf16 v[60:63], v[184:187], v[220:223], v[60:63]
	v_mfma_f32_16x16x32_bf16 v[52:55], v[200:203], v[220:223], v[52:55]
	v_mfma_f32_16x16x32_bf16 v[44:47], v[184:187], v[228:231], v[44:47]
	v_mfma_f32_16x16x32_bf16 v[36:39], v[200:203], v[228:231], v[36:39]
	v_mfma_f32_16x16x32_bf16 v[28:31], v[184:187], v[236:239], v[28:31]
	v_mfma_f32_16x16x32_bf16 v[20:23], v[200:203], v[236:239], v[20:23]
	s_setprio 0
	s_barrier
	s_add_i32 s35, s35, 2
	s_add_u32 s2, s2, 0x100
	s_addc_u32 s3, s3, 0
	s_add_u32 s33, s33, 0x100
	s_addc_u32 s34, s34, 0
	s_cmp_gt_u32 s35, 29
	s_cbranch_scc0 .LBB0_256
	s_and_b64 vcc, exec, s[12:13]
	s_cbranch_vccz .LBB0_259
	s_barrier

.LBB0_489:
	s_add_u32 s26, s22, 0xfff80080
	s_addc_u32 s27, s23, -1
	s_add_i32 s34, 0, 0x10000
	s_cmp_eq_u32 s33, 28
	s_cselect_b32 s39, s3, s27
	s_cselect_b32 s38, s6, s26
	s_cselect_b32 s27, s8, s17
	s_cselect_b32 s26, s9, s15
	s_add_i32 s53, 0, 0x14000
	v_add_u32_e32 v144, s34, v168
	v_add_u32_e32 v160, s53, v168
	ds_read_b128 v[4:7], v144
	ds_read_b128 v[8:11], v144 offset:1024
	ds_read_b128 v[140:143], v144 offset:2048
	ds_read_b128 v[144:147], v144 offset:3072
	ds_read_b128 v[172:175], v160
	ds_read_b128 v[176:179], v160 offset:1024
	ds_read_b128 v[180:183], v160 offset:2048
	ds_read_b128 v[184:187], v160 offset:3072
	v_lshl_add_u64 v[160:161], s[22:23], 0, v[156:157]
	s_add_i32 m0, s13, 0xc000
	ds_read_b128 v[188:191], v170
	ds_read_b128 v[192:195], v170 offset:1024
	ds_read_b128 v[196:199], v170 offset:2048
	ds_read_b128 v[200:203], v170 offset:3072
	ds_read_b128 v[204:207], v170 offset:4096
	ds_read_b128 v[212:215], v170 offset:5120
	ds_read_b128 v[216:219], v170 offset:6144
	ds_read_b128 v[220:223], v170 offset:7168
	global_load_lds_dwordx4 v[160:161], off
	v_lshl_add_u64 v[160:161], s[22:23], 0, v[158:159]
	s_add_i32 m0, s13, 0xe000
	s_nop 0
	global_load_lds_dwordx4 v[160:161], off
	s_waitcnt vmcnt(8)
	s_waitcnt lgkmcnt(0)
	s_barrier
	s_setprio 1
	v_mfma_f32_16x16x32_bf16 v[136:139], v[4:7], v[188:191], v[136:139]
	v_mfma_f32_16x16x32_bf16 v[132:135], v[140:143], v[188:191], v[132:135]
	v_mfma_f32_16x16x32_bf16 v[128:131], v[4:7], v[196:199], v[128:131]
	v_mfma_f32_16x16x32_bf16 v[120:123], v[140:143], v[196:199], v[120:123]
	v_mfma_f32_16x16x32_bf16 v[112:115], v[4:7], v[204:207], v[112:115]
	v_mfma_f32_16x16x32_bf16 v[104:107], v[140:143], v[204:207], v[104:107]
	v_mfma_f32_16x16x32_bf16 v[96:99], v[4:7], v[216:219], v[96:99]
	v_mfma_f32_16x16x32_bf16 v[88:91], v[140:143], v[216:219], v[88:91]
	v_mfma_f32_16x16x32_bf16 v[136:139], v[8:11], v[192:195], v[136:139]
	v_mfma_f32_16x16x32_bf16 v[132:135], v[144:147], v[192:195], v[132:135]
	v_mfma_f32_16x16x32_bf16 v[128:131], v[8:11], v[200:203], v[128:131]
	v_mfma_f32_16x16x32_bf16 v[120:123], v[144:147], v[200:203], v[120:123]
	v_mfma_f32_16x16x32_bf16 v[112:115], v[8:11], v[212:215], v[112:115]
	v_mfma_f32_16x16x32_bf16 v[104:107], v[144:147], v[212:215], v[104:107]
	v_mfma_f32_16x16x32_bf16 v[96:99], v[8:11], v[220:223], v[96:99]
	v_mfma_f32_16x16x32_bf16 v[88:91], v[144:147], v[220:223], v[88:91]
	v_mfma_f32_16x16x32_bf16 v[124:127], v[172:175], v[188:191], v[124:127]
	v_mfma_f32_16x16x32_bf16 v[116:119], v[180:183], v[188:191], v[116:119]
	v_mfma_f32_16x16x32_bf16 v[108:111], v[172:175], v[196:199], v[108:111]
	v_mfma_f32_16x16x32_bf16 v[100:103], v[180:183], v[196:199], v[100:103]
	v_mfma_f32_16x16x32_bf16 v[92:95], v[172:175], v[204:207], v[92:95]
	v_mfma_f32_16x16x32_bf16 v[84:87], v[180:183], v[204:207], v[84:87]
	v_mfma_f32_16x16x32_bf16 v[80:83], v[172:175], v[216:219], v[80:83]
	v_mfma_f32_16x16x32_bf16 v[76:79], v[180:183], v[216:219], v[76:79]
	v_mfma_f32_16x16x32_bf16 v[124:127], v[176:179], v[192:195], v[124:127]
	v_mfma_f32_16x16x32_bf16 v[116:119], v[184:187], v[192:195], v[116:119]
	v_mfma_f32_16x16x32_bf16 v[108:111], v[176:179], v[200:203], v[108:111]
	v_mfma_f32_16x16x32_bf16 v[100:103], v[184:187], v[200:203], v[100:103]
	v_mfma_f32_16x16x32_bf16 v[92:95], v[176:179], v[212:215], v[92:95]
	v_mfma_f32_16x16x32_bf16 v[84:87], v[184:187], v[212:215], v[84:87]
	v_mfma_f32_16x16x32_bf16 v[80:83], v[176:179], v[220:223], v[80:83]
	v_mfma_f32_16x16x32_bf16 v[76:79], v[184:187], v[220:223], v[76:79]
	s_setprio 0
	s_barrier
	s_add_i32 s34, s34, s7
	v_lshl_add_u64 v[160:161], s[26:27], 0, v[2:3]
	s_mov_b32 m0, s34
	ds_read_b128 v[188:191], v170 offset:16384
	ds_read_b128 v[192:195], v170 offset:17408
	ds_read_b128 v[196:199], v170 offset:18432
	ds_read_b128 v[200:203], v170 offset:19456
	ds_read_b128 v[204:207], v170 offset:20480
	ds_read_b128 v[212:215], v170 offset:21504
	ds_read_b128 v[216:219], v170 offset:22528
	ds_read_b128 v[220:223], v170 offset:23552
	global_load_lds_dwordx4 v[160:161], off
	s_add_i32 m0, s34, 0x2000
	s_add_u32 s34, s26, 0x80000
	v_lshl_add_u64 v[224:225], s[26:27], 0, v[148:149]
	s_addc_u32 s35, s27, 0
	s_add_i32 s53, s53, s7
	global_load_lds_dwordx4 v[224:225], off
	v_lshl_add_u64 v[226:227], s[34:35], 0, v[2:3]
	s_mov_b32 m0, s53
	v_lshl_add_u64 v[228:229], s[38:39], 0, v[150:151]
	global_load_lds_dwordx4 v[226:227], off
	v_lshl_add_u64 v[226:227], s[34:35], 0, v[148:149]
	s_add_i32 m0, s53, 0x2000
	s_nop 0
	global_load_lds_dwordx4 v[226:227], off
	v_lshl_add_u64 v[226:227], s[38:39], 0, v[152:153]
	s_mov_b32 m0, s13
	s_nop 0
	global_load_lds_dwordx4 v[226:227], off
	s_mov_b32 m0, s46
	s_nop 0
	global_load_lds_dwordx4 v[228:229], off
	s_waitcnt vmcnt(8)
	s_waitcnt lgkmcnt(0)
	s_barrier
	s_setprio 1
	v_mfma_f32_16x16x32_bf16 v[72:75], v[4:7], v[188:191], v[72:75]
	v_mfma_f32_16x16x32_bf16 v[68:71], v[140:143], v[188:191], v[68:71]
	v_mfma_f32_16x16x32_bf16 v[64:67], v[4:7], v[196:199], v[64:67]
	v_mfma_f32_16x16x32_bf16 v[56:59], v[140:143], v[196:199], v[56:59]
	v_mfma_f32_16x16x32_bf16 v[48:51], v[4:7], v[204:207], v[48:51]
	v_mfma_f32_16x16x32_bf16 v[40:43], v[140:143], v[204:207], v[40:43]
	v_mfma_f32_16x16x32_bf16 v[4:7], v[4:7], v[216:219], v[32:35]
	v_mfma_f32_16x16x32_bf16 v[72:75], v[8:11], v[192:195], v[72:75]
	v_mfma_f32_16x16x32_bf16 v[68:71], v[144:147], v[192:195], v[68:71]
	v_mfma_f32_16x16x32_bf16 v[64:67], v[8:11], v[200:203], v[64:67]
	v_mfma_f32_16x16x32_bf16 v[56:59], v[144:147], v[200:203], v[56:59]
	v_mfma_f32_16x16x32_bf16 v[48:51], v[8:11], v[212:215], v[48:51]
	v_mfma_f32_16x16x32_bf16 v[40:43], v[144:147], v[212:215], v[40:43]
	v_mfma_f32_16x16x32_bf16 v[4:7], v[8:11], v[220:223], v[4:7]
	v_mfma_f32_16x16x32_bf16 v[8:11], v[140:143], v[216:219], v[24:27]
	v_mfma_f32_16x16x32_bf16 v[8:11], v[144:147], v[220:223], v[8:11]
	v_mfma_f32_16x16x32_bf16 v[24:27], v[172:175], v[188:191], v[60:63]
	v_mfma_f32_16x16x32_bf16 v[60:63], v[176:179], v[192:195], v[24:27]
	v_mfma_f32_16x16x32_bf16 v[24:27], v[180:183], v[188:191], v[52:55]
	v_mfma_f32_16x16x32_bf16 v[52:55], v[184:187], v[192:195], v[24:27]
	v_mfma_f32_16x16x32_bf16 v[24:27], v[172:175], v[196:199], v[44:47]
	v_mfma_f32_16x16x32_bf16 v[44:47], v[176:179], v[200:203], v[24:27]
	v_mfma_f32_16x16x32_bf16 v[24:27], v[180:183], v[196:199], v[36:39]
	v_mfma_f32_16x16x32_bf16 v[36:39], v[184:187], v[200:203], v[24:27]
	v_mfma_f32_16x16x32_bf16 v[24:27], v[172:175], v[204:207], v[28:31]
	v_mfma_f32_16x16x32_bf16 v[20:23], v[180:183], v[204:207], v[20:23]
	v_mfma_f32_16x16x32_bf16 v[16:19], v[172:175], v[216:219], v[16:19]
	v_mfma_f32_16x16x32_bf16 v[12:15], v[180:183], v[216:219], v[12:15]
	v_mfma_f32_16x16x32_bf16 v[28:31], v[176:179], v[212:215], v[24:27]
	v_mfma_f32_16x16x32_bf16 v[20:23], v[184:187], v[212:215], v[20:23]
	v_mfma_f32_16x16x32_bf16 v[16:19], v[176:179], v[220:223], v[16:19]
	v_mfma_f32_16x16x32_bf16 v[12:15], v[184:187], v[220:223], v[12:15]
	s_setprio 0
	s_barrier
	s_add_i32 s53, 0, 0x18000
	s_add_i32 s54, 0, 0x1c000
	v_add_u32_e32 v144, s53, v168
	v_add_u32_e32 v171, s54, v168
	ds_read_b128 v[24:27], v144
	ds_read_b128 v[32:35], v144 offset:1024
	ds_read_b128 v[140:143], v144 offset:2048
	ds_read_b128 v[144:147], v144 offset:3072
	ds_read_b128 v[172:175], v171
	ds_read_b128 v[176:179], v171 offset:1024
	ds_read_b128 v[180:183], v171 offset:2048
	ds_read_b128 v[184:187], v171 offset:3072
	s_add_u32 s34, s38, 0x80000
	s_addc_u32 s35, s39, 0
	s_mov_b32 m0, s47
	v_lshl_add_u64 v[230:231], s[34:35], 0, v[152:153]
	ds_read_b128 v[188:191], v170 offset:32768
	ds_read_b128 v[192:195], v170 offset:33792
	ds_read_b128 v[196:199], v170 offset:34816
	ds_read_b128 v[200:203], v170 offset:35840
	ds_read_b128 v[204:207], v170 offset:36864
	ds_read_b128 v[212:215], v170 offset:37888
	ds_read_b128 v[216:219], v170 offset:38912
	ds_read_b128 v[220:223], v170 offset:39936
	global_load_lds_dwordx4 v[230:231], off
	v_lshl_add_u64 v[230:231], s[34:35], 0, v[150:151]
	s_mov_b32 m0, s48
	s_nop 0
	global_load_lds_dwordx4 v[230:231], off
	s_waitcnt vmcnt(8)
	s_waitcnt lgkmcnt(0)
	s_barrier
	s_setprio 1
	v_mfma_f32_16x16x32_bf16 v[136:139], v[24:27], v[188:191], v[136:139]
	v_mfma_f32_16x16x32_bf16 v[132:135], v[140:143], v[188:191], v[132:135]
	v_mfma_f32_16x16x32_bf16 v[128:131], v[24:27], v[196:199], v[128:131]
	v_mfma_f32_16x16x32_bf16 v[120:123], v[140:143], v[196:199], v[120:123]
	v_mfma_f32_16x16x32_bf16 v[112:115], v[24:27], v[204:207], v[112:115]
	v_mfma_f32_16x16x32_bf16 v[104:107], v[140:143], v[204:207], v[104:107]
	v_mfma_f32_16x16x32_bf16 v[96:99], v[24:27], v[216:219], v[96:99]
	v_mfma_f32_16x16x32_bf16 v[88:91], v[140:143], v[216:219], v[88:91]
	v_mfma_f32_16x16x32_bf16 v[136:139], v[32:35], v[192:195], v[136:139]
	v_mfma_f32_16x16x32_bf16 v[132:135], v[144:147], v[192:195], v[132:135]
	v_mfma_f32_16x16x32_bf16 v[128:131], v[32:35], v[200:203], v[128:131]
	v_mfma_f32_16x16x32_bf16 v[120:123], v[144:147], v[200:203], v[120:123]
	v_mfma_f32_16x16x32_bf16 v[112:115], v[32:35], v[212:215], v[112:115]
	v_mfma_f32_16x16x32_bf16 v[104:107], v[144:147], v[212:215], v[104:107]
	v_mfma_f32_16x16x32_bf16 v[96:99], v[32:35], v[220:223], v[96:99]
	v_mfma_f32_16x16x32_bf16 v[88:91], v[144:147], v[220:223], v[88:91]
	v_mfma_f32_16x16x32_bf16 v[124:127], v[172:175], v[188:191], v[124:127]
	v_mfma_f32_16x16x32_bf16 v[116:119], v[180:183], v[188:191], v[116:119]
	v_mfma_f32_16x16x32_bf16 v[108:111], v[172:175], v[196:199], v[108:111]
	v_mfma_f32_16x16x32_bf16 v[100:103], v[180:183], v[196:199], v[100:103]
	v_mfma_f32_16x16x32_bf16 v[92:95], v[172:175], v[204:207], v[92:95]
	v_mfma_f32_16x16x32_bf16 v[84:87], v[180:183], v[204:207], v[84:87]
	v_mfma_f32_16x16x32_bf16 v[80:83], v[172:175], v[216:219], v[80:83]
	v_mfma_f32_16x16x32_bf16 v[76:79], v[180:183], v[216:219], v[76:79]
	v_mfma_f32_16x16x32_bf16 v[124:127], v[176:179], v[192:195], v[124:127]
	v_mfma_f32_16x16x32_bf16 v[116:119], v[184:187], v[192:195], v[116:119]
	v_mfma_f32_16x16x32_bf16 v[108:111], v[176:179], v[200:203], v[108:111]
	v_mfma_f32_16x16x32_bf16 v[100:103], v[184:187], v[200:203], v[100:103]
	v_mfma_f32_16x16x32_bf16 v[92:95], v[176:179], v[212:215], v[92:95]
	v_mfma_f32_16x16x32_bf16 v[84:87], v[184:187], v[212:215], v[84:87]
	v_mfma_f32_16x16x32_bf16 v[80:83], v[176:179], v[220:223], v[80:83]
	v_mfma_f32_16x16x32_bf16 v[76:79], v[184:187], v[220:223], v[76:79]
	s_setprio 0
	s_barrier
	s_add_i32 s34, s53, s7
	v_lshl_add_u64 v[160:161], v[160:161], 0, s[30:31]
	s_mov_b32 m0, s34
	ds_read_b128 v[188:191], v170 offset:49152
	ds_read_b128 v[192:195], v170 offset:50176
	ds_read_b128 v[196:199], v170 offset:51200
	ds_read_b128 v[200:203], v170 offset:52224
	ds_read_b128 v[204:207], v170 offset:53248
	ds_read_b128 v[212:215], v170 offset:54272
	ds_read_b128 v[216:219], v170 offset:55296
	ds_read_b128 v[220:223], v170 offset:56320
	global_load_lds_dwordx4 v[160:161], off
	s_add_i32 m0, s34, 0x2000
	s_add_u32 s26, s26, 0x80080
	v_lshl_add_u64 v[160:161], v[224:225], 0, s[30:31]
	s_addc_u32 s27, s27, 0
	s_add_i32 s34, s54, s7
	global_load_lds_dwordx4 v[160:161], off
	v_lshl_add_u64 v[160:161], s[26:27], 0, v[2:3]
	s_mov_b32 m0, s34
	s_nop 0
	global_load_lds_dwordx4 v[160:161], off
	v_lshl_add_u64 v[160:161], s[26:27], 0, v[148:149]
	s_add_i32 m0, s34, 0x2000
	s_nop 0
	global_load_lds_dwordx4 v[160:161], off
	v_lshl_add_u64 v[160:161], v[226:227], 0, s[30:31]
	s_mov_b32 m0, s49
	s_nop 0
	global_load_lds_dwordx4 v[160:161], off
	v_lshl_add_u64 v[160:161], v[228:229], 0, s[30:31]
	s_mov_b32 m0, s50
	s_nop 0
	global_load_lds_dwordx4 v[160:161], off
	s_waitcnt vmcnt(8)
	s_waitcnt lgkmcnt(0)
	s_barrier
	s_setprio 1
	v_mfma_f32_16x16x32_bf16 v[72:75], v[24:27], v[188:191], v[72:75]
	v_mfma_f32_16x16x32_bf16 v[64:67], v[24:27], v[196:199], v[64:67]
	v_mfma_f32_16x16x32_bf16 v[48:51], v[24:27], v[204:207], v[48:51]
	v_mfma_f32_16x16x32_bf16 v[4:7], v[24:27], v[216:219], v[4:7]
	v_mfma_f32_16x16x32_bf16 v[72:75], v[32:35], v[192:195], v[72:75]
	v_mfma_f32_16x16x32_bf16 v[68:71], v[140:143], v[188:191], v[68:71]
	v_mfma_f32_16x16x32_bf16 v[64:67], v[32:35], v[200:203], v[64:67]
	v_mfma_f32_16x16x32_bf16 v[56:59], v[140:143], v[196:199], v[56:59]
	v_mfma_f32_16x16x32_bf16 v[48:51], v[32:35], v[212:215], v[48:51]
	v_mfma_f32_16x16x32_bf16 v[40:43], v[140:143], v[204:207], v[40:43]
	v_mfma_f32_16x16x32_bf16 v[32:35], v[32:35], v[220:223], v[4:7]
	v_mfma_f32_16x16x32_bf16 v[4:7], v[140:143], v[216:219], v[8:11]
	v_mfma_f32_16x16x32_bf16 v[68:71], v[144:147], v[192:195], v[68:71]
	v_mfma_f32_16x16x32_bf16 v[56:59], v[144:147], v[200:203], v[56:59]
	v_mfma_f32_16x16x32_bf16 v[40:43], v[144:147], v[212:215], v[40:43]
	v_mfma_f32_16x16x32_bf16 v[24:27], v[144:147], v[220:223], v[4:7]
	v_mfma_f32_16x16x32_bf16 v[4:7], v[172:175], v[188:191], v[60:63]
	v_mfma_f32_16x16x32_bf16 v[60:63], v[176:179], v[192:195], v[4:7]
	v_mfma_f32_16x16x32_bf16 v[4:7], v[180:183], v[188:191], v[52:55]
	v_mfma_f32_16x16x32_bf16 v[52:55], v[184:187], v[192:195], v[4:7]
	v_mfma_f32_16x16x32_bf16 v[4:7], v[172:175], v[196:199], v[44:47]
	v_mfma_f32_16x16x32_bf16 v[44:47], v[176:179], v[200:203], v[4:7]
	v_mfma_f32_16x16x32_bf16 v[4:7], v[180:183], v[196:199], v[36:39]
	v_mfma_f32_16x16x32_bf16 v[36:39], v[184:187], v[200:203], v[4:7]
	v_mfma_f32_16x16x32_bf16 v[4:7], v[172:175], v[204:207], v[28:31]
	v_mfma_f32_16x16x32_bf16 v[28:31], v[176:179], v[212:215], v[4:7]
	v_mfma_f32_16x16x32_bf16 v[4:7], v[180:183], v[204:207], v[20:23]
	v_mfma_f32_16x16x32_bf16 v[20:23], v[184:187], v[212:215], v[4:7]
	v_mfma_f32_16x16x32_bf16 v[4:7], v[172:175], v[216:219], v[16:19]
	v_mfma_f32_16x16x32_bf16 v[16:19], v[176:179], v[220:223], v[4:7]
	v_mfma_f32_16x16x32_bf16 v[4:7], v[180:183], v[216:219], v[12:15]
	v_mfma_f32_16x16x32_bf16 v[12:15], v[184:187], v[220:223], v[4:7]
	s_setprio 0
	s_barrier
	s_add_i32 s33, s33, 2
	s_add_u32 s22, s22, 0x100
	s_addc_u32 s23, s23, 0
	s_add_u32 s15, s15, 0x100
	s_addc_u32 s17, s17, 0
	s_cmp_gt_u32 s33, 29
	s_cbranch_scc0 .LBB0_489
	s_and_b64 vcc, exec, s[4:5]
	s_cbranch_vccz .LBB0_492
	s_barrier

.LBB0_832:
	s_add_i32 s28, s9, 2
	s_add_u32 s22, s2, 0x80
	s_addc_u32 s23, s3, 0
	s_add_i32 s29, 0, 0x10000
	s_cmp_eq_u32 s52, s9
	s_cselect_b32 s23, s1, s23
	s_cselect_b32 s22, s0, s22
	v_add_u32_e32 v2, s29, v147
	s_cselect_b32 s35, s21, s8
	s_cselect_b32 s34, s20, s7
	s_add_i32 s9, 0, 0x14000
	ds_read_b128 v[152:155], v2
	ds_read_b128 v[156:159], v2 offset:1024
	ds_read_b128 v[160:163], v2 offset:2048
	ds_read_b128 v[168:171], v2 offset:3072
	v_add_u32_e32 v2, s9, v147
	ds_read_b128 v[172:175], v2
	ds_read_b128 v[176:179], v2 offset:1024
	ds_read_b128 v[180:183], v2 offset:2048
	ds_read_b128 v[184:187], v2 offset:3072
	v_lshl_add_u64 v[144:145], s[2:3], 0, v[140:141]
	s_add_i32 m0, s47, 0xc000
	ds_read_b128 v[188:191], v150
	ds_read_b128 v[192:195], v150 offset:1024
	ds_read_b128 v[196:199], v150 offset:2048
	ds_read_b128 v[200:203], v150 offset:3072
	ds_read_b128 v[204:207], v150 offset:4096
	ds_read_b128 v[210:213], v150 offset:5120
	ds_read_b128 v[214:217], v150 offset:6144
	ds_read_b128 v[218:221], v150 offset:7168
	global_load_lds_dwordx4 v[144:145], off
	v_lshl_add_u64 v[144:145], s[2:3], 0, v[142:143]
	s_add_i32 m0, s47, 0xe000
	s_nop 0
	global_load_lds_dwordx4 v[144:145], off
	s_waitcnt vmcnt(8)
	s_waitcnt lgkmcnt(0)
	s_barrier
	s_setprio 1
	v_mfma_f32_16x16x32_bf16 v[128:131], v[152:155], v[188:191], v[128:131]
	v_mfma_f32_16x16x32_bf16 v[124:127], v[160:163], v[188:191], v[124:127]
	v_mfma_f32_16x16x32_bf16 v[112:115], v[152:155], v[196:199], v[112:115]
	v_mfma_f32_16x16x32_bf16 v[108:111], v[160:163], v[196:199], v[108:111]
	v_mfma_f32_16x16x32_bf16 v[96:99], v[152:155], v[204:207], v[96:99]
	v_mfma_f32_16x16x32_bf16 v[92:95], v[160:163], v[204:207], v[92:95]
	v_mfma_f32_16x16x32_bf16 v[80:83], v[152:155], v[214:217], v[80:83]
	v_mfma_f32_16x16x32_bf16 v[76:79], v[160:163], v[214:217], v[76:79]
	v_mfma_f32_16x16x32_bf16 v[128:131], v[156:159], v[192:195], v[128:131]
	v_mfma_f32_16x16x32_bf16 v[124:127], v[168:171], v[192:195], v[124:127]
	v_mfma_f32_16x16x32_bf16 v[112:115], v[156:159], v[200:203], v[112:115]
	v_mfma_f32_16x16x32_bf16 v[108:111], v[168:171], v[200:203], v[108:111]
	v_mfma_f32_16x16x32_bf16 v[96:99], v[156:159], v[210:213], v[96:99]
	v_mfma_f32_16x16x32_bf16 v[92:95], v[168:171], v[210:213], v[92:95]
	v_mfma_f32_16x16x32_bf16 v[80:83], v[156:159], v[218:221], v[80:83]
	v_mfma_f32_16x16x32_bf16 v[76:79], v[168:171], v[218:221], v[76:79]
	v_mfma_f32_16x16x32_bf16 v[120:123], v[172:175], v[188:191], v[120:123]
	v_mfma_f32_16x16x32_bf16 v[116:119], v[180:183], v[188:191], v[116:119]
	v_mfma_f32_16x16x32_bf16 v[104:107], v[172:175], v[196:199], v[104:107]
	v_mfma_f32_16x16x32_bf16 v[100:103], v[180:183], v[196:199], v[100:103]
	v_mfma_f32_16x16x32_bf16 v[88:91], v[172:175], v[204:207], v[88:91]
	v_mfma_f32_16x16x32_bf16 v[84:87], v[180:183], v[204:207], v[84:87]
	v_mfma_f32_16x16x32_bf16 v[72:75], v[172:175], v[214:217], v[72:75]
	v_mfma_f32_16x16x32_bf16 v[68:71], v[180:183], v[214:217], v[68:71]
	v_mfma_f32_16x16x32_bf16 v[120:123], v[176:179], v[192:195], v[120:123]
	v_mfma_f32_16x16x32_bf16 v[116:119], v[184:187], v[192:195], v[116:119]
	v_mfma_f32_16x16x32_bf16 v[104:107], v[176:179], v[200:203], v[104:107]
	v_mfma_f32_16x16x32_bf16 v[100:103], v[184:187], v[200:203], v[100:103]
	v_mfma_f32_16x16x32_bf16 v[88:91], v[176:179], v[210:213], v[88:91]
	v_mfma_f32_16x16x32_bf16 v[84:87], v[184:187], v[210:213], v[84:87]
	v_mfma_f32_16x16x32_bf16 v[72:75], v[176:179], v[218:221], v[72:75]
	v_mfma_f32_16x16x32_bf16 v[68:71], v[184:187], v[218:221], v[68:71]
	s_setprio 0
	s_barrier
	s_add_i32 s29, s29, s26
	v_lshl_add_u64 v[144:145], s[34:35], 0, v[136:137]
	s_mov_b32 m0, s29
	ds_read_b128 v[188:191], v150 offset:16384
	ds_read_b128 v[192:195], v150 offset:17408
	ds_read_b128 v[196:199], v150 offset:18432
	ds_read_b128 v[200:203], v150 offset:19456
	ds_read_b128 v[204:207], v150 offset:20480
	ds_read_b128 v[210:213], v150 offset:21504
	ds_read_b128 v[214:217], v150 offset:22528
	ds_read_b128 v[218:221], v150 offset:23552
	global_load_lds_dwordx4 v[144:145], off
	s_add_i32 m0, s29, 0x2000
	v_lshl_add_u64 v[222:223], s[34:35], 0, v[132:133]
	s_add_u32 s34, s34, s16
	s_addc_u32 s35, s35, 0
	s_add_i32 s9, s9, s26
	global_load_lds_dwordx4 v[222:223], off
	v_lshl_add_u64 v[224:225], s[34:35], 0, v[136:137]
	s_mov_b32 m0, s9
	v_lshl_add_u64 v[226:227], s[34:35], 0, v[132:133]
	global_load_lds_dwordx4 v[224:225], off
	s_add_i32 m0, s9, 0x2000
	v_lshl_add_u64 v[228:229], s[22:23], 0, v[138:139]
	global_load_lds_dwordx4 v[226:227], off
	s_mov_b32 m0, s47
	v_lshl_add_u64 v[230:231], s[22:23], 0, v[134:135]
	global_load_lds_dwordx4 v[228:229], off
	s_mov_b32 m0, s48
	s_nop 0
	global_load_lds_dwordx4 v[230:231], off
	s_waitcnt vmcnt(8)
	s_waitcnt lgkmcnt(0)
	s_barrier
	s_setprio 1
	v_mfma_f32_16x16x32_bf16 v[64:67], v[152:155], v[188:191], v[64:67]
	v_mfma_f32_16x16x32_bf16 v[60:63], v[160:163], v[188:191], v[60:63]
	v_mfma_f32_16x16x32_bf16 v[48:51], v[152:155], v[196:199], v[48:51]
	v_mfma_f32_16x16x32_bf16 v[44:47], v[160:163], v[196:199], v[44:47]
	v_mfma_f32_16x16x32_bf16 v[32:35], v[152:155], v[204:207], v[32:35]
	v_mfma_f32_16x16x32_bf16 v[28:31], v[160:163], v[204:207], v[28:31]
	v_mfma_f32_16x16x32_bf16 v[16:19], v[152:155], v[214:217], v[16:19]
	v_mfma_f32_16x16x32_bf16 v[12:15], v[160:163], v[214:217], v[12:15]
	v_mfma_f32_16x16x32_bf16 v[64:67], v[156:159], v[192:195], v[64:67]
	v_mfma_f32_16x16x32_bf16 v[60:63], v[168:171], v[192:195], v[60:63]
	v_mfma_f32_16x16x32_bf16 v[48:51], v[156:159], v[200:203], v[48:51]
	v_mfma_f32_16x16x32_bf16 v[44:47], v[168:171], v[200:203], v[44:47]
	v_mfma_f32_16x16x32_bf16 v[32:35], v[156:159], v[210:213], v[32:35]
	v_mfma_f32_16x16x32_bf16 v[28:31], v[168:171], v[210:213], v[28:31]
	v_mfma_f32_16x16x32_bf16 v[16:19], v[156:159], v[218:221], v[16:19]
	v_mfma_f32_16x16x32_bf16 v[12:15], v[168:171], v[218:221], v[12:15]
	v_mfma_f32_16x16x32_bf16 v[56:59], v[172:175], v[188:191], v[56:59]
	v_mfma_f32_16x16x32_bf16 v[52:55], v[180:183], v[188:191], v[52:55]
	v_mfma_f32_16x16x32_bf16 v[40:43], v[172:175], v[196:199], v[40:43]
	v_mfma_f32_16x16x32_bf16 v[36:39], v[180:183], v[196:199], v[36:39]
	v_mfma_f32_16x16x32_bf16 v[24:27], v[172:175], v[204:207], v[24:27]
	v_mfma_f32_16x16x32_bf16 v[20:23], v[180:183], v[204:207], v[20:23]
	v_mfma_f32_16x16x32_bf16 v[8:11], v[172:175], v[214:217], v[8:11]
	v_mfma_f32_16x16x32_bf16 v[4:7], v[180:183], v[214:217], v[4:7]
	v_mfma_f32_16x16x32_bf16 v[56:59], v[176:179], v[192:195], v[56:59]
	v_mfma_f32_16x16x32_bf16 v[52:55], v[184:187], v[192:195], v[52:55]
	v_mfma_f32_16x16x32_bf16 v[40:43], v[176:179], v[200:203], v[40:43]
	v_mfma_f32_16x16x32_bf16 v[36:39], v[184:187], v[200:203], v[36:39]
	v_mfma_f32_16x16x32_bf16 v[24:27], v[176:179], v[210:213], v[24:27]
	v_mfma_f32_16x16x32_bf16 v[20:23], v[184:187], v[210:213], v[20:23]
	v_mfma_f32_16x16x32_bf16 v[8:11], v[176:179], v[218:221], v[8:11]
	v_mfma_f32_16x16x32_bf16 v[4:7], v[184:187], v[218:221], v[4:7]
	s_setprio 0
	s_barrier
	s_add_i32 s9, 0, 0x18000
	v_add_u32_e32 v2, s9, v147
	s_add_i32 s29, 0, 0x1c000
	ds_read_b128 v[152:155], v2
	ds_read_b128 v[156:159], v2 offset:1024
	ds_read_b128 v[160:163], v2 offset:2048
	ds_read_b128 v[168:171], v2 offset:3072
	v_add_u32_e32 v2, s29, v147
	ds_read_b128 v[172:175], v2
	ds_read_b128 v[176:179], v2 offset:1024
	ds_read_b128 v[180:183], v2 offset:2048
	ds_read_b128 v[184:187], v2 offset:3072
	s_add_u32 s22, s22, s16
	s_addc_u32 s23, s23, 0
	s_mov_b32 m0, s49
	v_lshl_add_u64 v[232:233], s[22:23], 0, v[138:139]
	ds_read_b128 v[188:191], v150 offset:32768
	ds_read_b128 v[192:195], v150 offset:33792
	ds_read_b128 v[196:199], v150 offset:34816
	ds_read_b128 v[200:203], v150 offset:35840
	ds_read_b128 v[204:207], v150 offset:36864
	ds_read_b128 v[210:213], v150 offset:37888
	ds_read_b128 v[214:217], v150 offset:38912
	ds_read_b128 v[218:221], v150 offset:39936
	global_load_lds_dwordx4 v[232:233], off
	v_lshl_add_u64 v[232:233], s[22:23], 0, v[134:135]
	s_mov_b32 m0, s50
	s_nop 0
	global_load_lds_dwordx4 v[232:233], off
	s_waitcnt vmcnt(8)
	s_waitcnt lgkmcnt(0)
	s_barrier
	s_setprio 1
	v_mfma_f32_16x16x32_bf16 v[128:131], v[152:155], v[188:191], v[128:131]
	v_mfma_f32_16x16x32_bf16 v[124:127], v[160:163], v[188:191], v[124:127]
	v_mfma_f32_16x16x32_bf16 v[112:115], v[152:155], v[196:199], v[112:115]
	v_mfma_f32_16x16x32_bf16 v[108:111], v[160:163], v[196:199], v[108:111]
	v_mfma_f32_16x16x32_bf16 v[96:99], v[152:155], v[204:207], v[96:99]
	v_mfma_f32_16x16x32_bf16 v[92:95], v[160:163], v[204:207], v[92:95]
	v_mfma_f32_16x16x32_bf16 v[80:83], v[152:155], v[214:217], v[80:83]
	v_mfma_f32_16x16x32_bf16 v[76:79], v[160:163], v[214:217], v[76:79]
	v_mfma_f32_16x16x32_bf16 v[128:131], v[156:159], v[192:195], v[128:131]
	v_mfma_f32_16x16x32_bf16 v[124:127], v[168:171], v[192:195], v[124:127]
	v_mfma_f32_16x16x32_bf16 v[112:115], v[156:159], v[200:203], v[112:115]
	v_mfma_f32_16x16x32_bf16 v[108:111], v[168:171], v[200:203], v[108:111]
	v_mfma_f32_16x16x32_bf16 v[96:99], v[156:159], v[210:213], v[96:99]
	v_mfma_f32_16x16x32_bf16 v[92:95], v[168:171], v[210:213], v[92:95]
	v_mfma_f32_16x16x32_bf16 v[80:83], v[156:159], v[218:221], v[80:83]
	v_mfma_f32_16x16x32_bf16 v[76:79], v[168:171], v[218:221], v[76:79]
	v_mfma_f32_16x16x32_bf16 v[120:123], v[172:175], v[188:191], v[120:123]
	v_mfma_f32_16x16x32_bf16 v[116:119], v[180:183], v[188:191], v[116:119]
	v_mfma_f32_16x16x32_bf16 v[104:107], v[172:175], v[196:199], v[104:107]
	v_mfma_f32_16x16x32_bf16 v[100:103], v[180:183], v[196:199], v[100:103]
	v_mfma_f32_16x16x32_bf16 v[88:91], v[172:175], v[204:207], v[88:91]
	v_mfma_f32_16x16x32_bf16 v[84:87], v[180:183], v[204:207], v[84:87]
	v_mfma_f32_16x16x32_bf16 v[72:75], v[172:175], v[214:217], v[72:75]
	v_mfma_f32_16x16x32_bf16 v[68:71], v[180:183], v[214:217], v[68:71]
	v_mfma_f32_16x16x32_bf16 v[120:123], v[176:179], v[192:195], v[120:123]
	v_mfma_f32_16x16x32_bf16 v[116:119], v[184:187], v[192:195], v[116:119]
	v_mfma_f32_16x16x32_bf16 v[104:107], v[176:179], v[200:203], v[104:107]
	v_mfma_f32_16x16x32_bf16 v[100:103], v[184:187], v[200:203], v[100:103]
	v_mfma_f32_16x16x32_bf16 v[88:91], v[176:179], v[210:213], v[88:91]
	v_mfma_f32_16x16x32_bf16 v[84:87], v[184:187], v[210:213], v[84:87]
	v_mfma_f32_16x16x32_bf16 v[72:75], v[176:179], v[218:221], v[72:75]
	v_mfma_f32_16x16x32_bf16 v[68:71], v[184:187], v[218:221], v[68:71]
	s_setprio 0
	s_barrier
	s_add_i32 s9, s9, s26
	v_lshl_add_u64 v[144:145], v[144:145], 0, s[30:31]
	s_mov_b32 m0, s9
	ds_read_b128 v[188:191], v150 offset:49152
	ds_read_b128 v[192:195], v150 offset:50176
	ds_read_b128 v[196:199], v150 offset:51200
	ds_read_b128 v[200:203], v150 offset:52224
	ds_read_b128 v[204:207], v150 offset:53248
	ds_read_b128 v[210:213], v150 offset:54272
	ds_read_b128 v[214:217], v150 offset:55296
	ds_read_b128 v[218:221], v150 offset:56320
	global_load_lds_dwordx4 v[144:145], off
	v_lshl_add_u64 v[144:145], v[222:223], 0, s[30:31]
	s_add_i32 m0, s9, 0x2000
	s_add_i32 s9, s29, s26
	global_load_lds_dwordx4 v[144:145], off
	v_lshl_add_u64 v[144:145], v[224:225], 0, s[30:31]
	s_mov_b32 m0, s9
	s_nop 0
	global_load_lds_dwordx4 v[144:145], off
	v_lshl_add_u64 v[144:145], v[226:227], 0, s[30:31]
	s_add_i32 m0, s9, 0x2000
	s_nop 0
	global_load_lds_dwordx4 v[144:145], off
	v_lshl_add_u64 v[144:145], v[228:229], 0, s[30:31]
	s_mov_b32 m0, s53
	s_nop 0
	global_load_lds_dwordx4 v[144:145], off
	v_lshl_add_u64 v[144:145], v[230:231], 0, s[30:31]
	s_mov_b32 m0, s54
	s_nop 0
	global_load_lds_dwordx4 v[144:145], off
	s_waitcnt vmcnt(8)
	s_waitcnt lgkmcnt(0)
	s_barrier
	s_setprio 1
	v_mfma_f32_16x16x32_bf16 v[64:67], v[152:155], v[188:191], v[64:67]
	v_mfma_f32_16x16x32_bf16 v[60:63], v[160:163], v[188:191], v[60:63]
	v_mfma_f32_16x16x32_bf16 v[48:51], v[152:155], v[196:199], v[48:51]
	v_mfma_f32_16x16x32_bf16 v[44:47], v[160:163], v[196:199], v[44:47]
	v_mfma_f32_16x16x32_bf16 v[32:35], v[152:155], v[204:207], v[32:35]
	v_mfma_f32_16x16x32_bf16 v[28:31], v[160:163], v[204:207], v[28:31]
	v_mfma_f32_16x16x32_bf16 v[16:19], v[152:155], v[214:217], v[16:19]
	v_mfma_f32_16x16x32_bf16 v[12:15], v[160:163], v[214:217], v[12:15]
	v_mfma_f32_16x16x32_bf16 v[64:67], v[156:159], v[192:195], v[64:67]
	v_mfma_f32_16x16x32_bf16 v[60:63], v[168:171], v[192:195], v[60:63]
	v_mfma_f32_16x16x32_bf16 v[48:51], v[156:159], v[200:203], v[48:51]
	v_mfma_f32_16x16x32_bf16 v[44:47], v[168:171], v[200:203], v[44:47]
	v_mfma_f32_16x16x32_bf16 v[32:35], v[156:159], v[210:213], v[32:35]
	v_mfma_f32_16x16x32_bf16 v[28:31], v[168:171], v[210:213], v[28:31]
	v_mfma_f32_16x16x32_bf16 v[16:19], v[156:159], v[218:221], v[16:19]
	v_mfma_f32_16x16x32_bf16 v[12:15], v[168:171], v[218:221], v[12:15]
	v_mfma_f32_16x16x32_bf16 v[56:59], v[172:175], v[188:191], v[56:59]
	v_mfma_f32_16x16x32_bf16 v[52:55], v[180:183], v[188:191], v[52:55]
	v_mfma_f32_16x16x32_bf16 v[40:43], v[172:175], v[196:199], v[40:43]
	v_mfma_f32_16x16x32_bf16 v[36:39], v[180:183], v[196:199], v[36:39]
	v_mfma_f32_16x16x32_bf16 v[24:27], v[172:175], v[204:207], v[24:27]
	v_mfma_f32_16x16x32_bf16 v[20:23], v[180:183], v[204:207], v[20:23]
	v_mfma_f32_16x16x32_bf16 v[8:11], v[172:175], v[214:217], v[8:11]
	v_mfma_f32_16x16x32_bf16 v[4:7], v[180:183], v[214:217], v[4:7]
	v_mfma_f32_16x16x32_bf16 v[56:59], v[176:179], v[192:195], v[56:59]
	v_mfma_f32_16x16x32_bf16 v[52:55], v[184:187], v[192:195], v[52:55]
	v_mfma_f32_16x16x32_bf16 v[40:43], v[176:179], v[200:203], v[40:43]
	v_mfma_f32_16x16x32_bf16 v[36:39], v[184:187], v[200:203], v[36:39]
	v_mfma_f32_16x16x32_bf16 v[24:27], v[176:179], v[210:213], v[24:27]
	v_mfma_f32_16x16x32_bf16 v[20:23], v[184:187], v[210:213], v[20:23]
	v_mfma_f32_16x16x32_bf16 v[8:11], v[176:179], v[218:221], v[8:11]
	v_mfma_f32_16x16x32_bf16 v[4:7], v[184:187], v[218:221], v[4:7]
	s_setprio 0
	s_barrier
	s_add_u32 s2, s2, 0x100
	s_addc_u32 s3, s3, 0
	s_add_u32 s7, s7, 0x100
	s_addc_u32 s8, s8, 0
	s_cmp_ge_u32 s28, s51
	s_mov_b32 s9, s28
	s_cbranch_scc0 .LBB0_832
	s_and_b64 vcc, exec, s[18:19]
	s_cbranch_vccz .LBB0_835
	s_barrier
